# attention unit prologue: tile-0 K/V also staged by LDS-DMA at unit start (no VGPR round trip / ds_write before first barrier)
# baseline (speedup 1.0000x reference)
; DI int v_st(int k, int c) { const int kk = (k & ~0xC) | ((k & 4) << 1) | ((k & 8) >> 1); return ((kk >> 3) * 4 + (c >> 5)) * 512 + ((kk & 7) * 32 + (c & 31)) * 2; }
; DI int v_rd_base(int lane) { return ((lane & 3) << 3) | (((lane >> 2) & 3) << 6) | (((lane >> 4) & 1) << 5) | (((lane >> 5) & 1) << 8); }
; #define SLOAD(i, k0) do { sr_[i].vs0 = *(const bf16x8*)(&Vh[(long)((k0) + sr) * LDA_ + sc]); sr_[i].vs1 = *(const bf16x8*)(&Vh[(long)((k0) + 32 + sr) * LDA_ + sc]); \
;     sr_[i].ks0 = *(const bf16x8*)(&Kh[(long)((k0) + sr) * LDA_ + sc]); sr_[i].ks1 = *(const bf16x8*)(&Kh[(long)((k0) + 32 + sr) * LDA_ + sc]); } while (0)
; #define SWRITE(b, i) do { *(bf16x8*)(V_lds + (b) * SHM_V + vst0) = sr_[i].vs0;          \
;     *(bf16x8*)(V_lds + (b) * SHM_V + vst1) = sr_[i].vs1; int kc = sc * 2;               \
;     *(bf16x8*)(K_lds + (b) * SHM_K + KSWZ(sr, kc)) = sr_[i].ks0;                       \
;     *(bf16x8*)(K_lds + (b) * SHM_K + KSWZ(32 + sr, kc)) = sr_[i].ks1; } while (0)
; DI void attn_unit(const bf16_t* __restrict__ Qb, const bf16_t* __restrict__ Kh, const bf16_t* __restrict__ Vh, bf16_t* __restrict__ Ob, const float* __restrict__ onw, int seq, char* lds) {
;     int tid_ = threadIdx.x; asm volatile("" : "+v"(tid_));
;     const int tid = tid_, wid = tid >> 6, lane = tid & 63, r32 = lane & 31, hi = lane >> 5;
;     char* V_lds = lds; char* K_lds = lds + 2 * SHM_V;
;     float* wsf = (float*)(lds + 2 * SHM_V + 2 * SHM_K) + wid * 64; float* li_l = wsf; float* al_l = wsf + 32;
;     float m_reg = 0.f, l_reg = 0; f32x16 o[4]; bf16x8 qr[8];
; #pragma unroll
;     for (int d = 0; d < 4; ++d)
; #pragma unroll
;         for (int i = 0; i < 16; ++i) o[d][i] = 0.f;
;     const bf16_t* Qw = Qb + (long)((wid & 3) * 32 + r32) * LDA_ + (wid >> 2) * 128 + hi * 8;
; #pragma unroll
;     for (int d0 = 0; d0 < 8; ++d0) qr[d0] = *(const bf16x8*)(Qw + d0 * 16);
;     const int sr = tid >> 4, sc = (tid & 15) * 8, vst0 = v_st(sr, sc), vst1 = v_st(32 + sr, sc);
;     const int vb0 = (int)(uintptr_t)V_lds + v_rd_base(lane);
;     struct { bf16x8 vs0, vs1, ks0, ks1; } sr_[1];
;     ...
;     f32x16 pA0, pA1, pB0, pB1; float alA, alB; bf16x8 pa0, pa1, pa2, pa3; const int NT = seq / 64;
;     constexpr int SE = 0, SO = 0;
;     SLOAD(SE, 0); asm volatile("s_waitcnt vmcnt(0)" ::: "memory"); SWRITE(0, SE); __syncthreads();
.LBB0_579:
	s_and_b32 s12, s14, 1
	s_lshl_b32 s2, s15, 7
	s_add_u32 s2, s68, s2
	s_addc_u32 s3, s69, 0
	s_lshl_b64 s[66:67], s[2:3], 10
	s_lshl_b64 s[2:3], s[2:3], 11
	s_add_u32 s2, s30, s2
	s_addc_u32 s3, s31, s3
	s_lshl_b32 s72, s12, 8
	s_lshl_b32 s12, s12, 9
	s_add_u32 s2, s2, s12
	s_waitcnt vmcnt(0)
	v_mov_b32_e32 v80, v192
	s_addc_u32 s3, s3, 0
	s_lshl_b64 s[14:15], s[68:69], 11
	s_add_u32 s12, s30, s14
	v_ashrrev_i32_e32 v48, 4, v80
	v_lshlrev_b32_e32 v20, 3, v80
	v_add_u32_e32 v16, 32, v48
	s_addc_u32 s15, s31, s15
	v_and_b32_e32 v0, 0x78, v20
	v_ashrrev_i32_e32 v49, 31, v48
	v_ashrrev_i32_e32 v17, 31, v16
	s_add_u32 s14, s12, s72
	v_lshlrev_b32_e32 v21, 1, v0
	v_lshlrev_b64 v[0:1], 11, v[48:49]
	v_lshlrev_b64 v[4:5], 11, v[16:17]
	s_addc_u32 s15, s15, 0
	v_or_b32_e32 v0, v0, v21
	v_or_b32_e32 v4, v4, v21
	v_lshl_add_u64 v[50:51], s[14:15], 0, v[0:1]
	v_lshl_add_u64 v[12:13], s[14:15], 0, v[4:5]
	s_add_u32 s98, s14, 0x20400
	s_addc_u32 s99, s15, 0
	v_readfirstlane_b32 s100, v80
	v_and_b32_e32 v250, 63, v80
	v_lshrrev_b32_e32 v251, 6, v80
	v_lshrrev_b32_e32 v252, 4, v250
	v_and_b32_e32 v253, 1, v251
	v_lshl_add_u32 v253, v253, 2, v252
	v_and_b32_e32 v246, 15, v250
	v_xor_b32_e32 v246, v246, v253
	v_lshlrev_b32_e32 v246, 4, v246
	v_lshl_add_u32 v252, v251, 2, v252
	v_lshl_add_u32 v246, v252, 11, v246
	v_add_u32_e32 v246, 0x20000, v246
	v_add_u32_e32 v247, 0x10000, v246
	v_bfe_u32 v252, v250, 2, 3
	v_and_b32_e32 v253, 3, v252
	v_lshrrev_b32_e32 v252, 2, v252
	v_lshl_add_u32 v253, v252, 3, v253
	v_bfe_u32 v252, v251, 1, 1
	v_lshl_add_u32 v253, v252, 2, v253
	v_bfe_u32 v252, v251, 2, 1
	v_lshl_add_u32 v253, v252, 4, v253
	v_lshlrev_b32_e32 v248, 11, v253
	v_and_b32_e32 v252, 1, v251
	v_lshlrev_b32_e32 v252, 1, v252
	v_lshrrev_b32_e32 v253, 5, v250
	v_add_u32_e32 v252, v252, v253
	v_and_b32_e32 v253, 3, v250
	v_lshl_add_u32 v252, v252, 2, v253
	v_lshl_add_u32 v248, v252, 4, v248
	v_add_u32_e32 v248, 0x200, v248
	v_add_u32_e32 v249, 0x10000, v248
	s_lshl_b32 s100, s100, 4
	s_sub_u32 s98, s98, 0x40000
	s_subb_u32 s99, s99, 0
	s_add_u32 m0, s100, 0x8000
	s_nop 0
	global_load_lds_dwordx4 v246, s[98:99]
	s_add_u32 m0, s100, 0xa000
	s_nop 0
	global_load_lds_dwordx4 v247, s[98:99]
	s_add_u32 s98, s98, 0x20000
	s_addc_u32 s99, s99, 0
	s_add_u32 m0, s100, 0x0
	s_nop 0
	global_load_lds_dwordx4 v248, s[98:99]
	s_add_u32 m0, s100, 0x2000
	s_nop 0
	global_load_lds_dwordx4 v249, s[98:99]
	s_add_u32 m0, s100, 0xc000
	s_nop 0
	global_load_lds_dwordx4 v246, s[98:99]
	s_add_u32 m0, s100, 0xe000
	s_nop 0
	global_load_lds_dwordx4 v247, s[98:99]
	s_add_u32 s98, s98, 0x20000
	s_addc_u32 s99, s99, 0
	s_add_u32 m0, s100, 0x4000
	s_nop 0
	global_load_lds_dwordx4 v248, s[98:99]
	s_add_u32 m0, s100, 0x6000
	s_nop 0
	global_load_lds_dwordx4 v249, s[98:99]
	s_nop 0
	v_lshrrev_b32_e32 v17, 1, v80
	v_and_b32_e32 v155, 31, v80
	v_and_b32_e32 v170, 0x60, v17
	v_or_b32_e32 v17, v170, v155
	v_lshlrev_b32_e32 v184, 11, v17
	v_ashrrev_i32_e32 v17, 1, v80
	v_and_b32_e32 v148, 0xffffff80, v17
	v_bfe_u32 v151, v80, 5, 1
	v_lshl_add_u64 v[18:19], s[2:3], 0, v[184:185]
	v_ashrrev_i32_e32 v149, 31, v148
	v_lshl_add_u64 v[18:19], v[148:149], 1, v[18:19]
	v_lshlrev_b32_e32 v184, 4, v151
	v_lshl_add_u64 v[18:19], v[18:19], 0, v[184:185]
	global_load_dwordx4 v[140:143], v[18:19], off
	global_load_dwordx4 v[136:139], v[18:19], off offset:32
	global_load_dwordx4 v[132:135], v[18:19], off offset:64
	global_load_dwordx4 v[128:131], v[18:19], off offset:96
	global_load_dwordx4 v[124:127], v[18:19], off offset:128
	global_load_dwordx4 v[120:123], v[18:19], off offset:160
	global_load_dwordx4 v[116:119], v[18:19], off offset:192
	global_load_dwordx4 v[112:115], v[18:19], off offset:224
	v_and_b32_e32 v22, 0xfffff0, v48
	v_lshlrev_b32_e32 v23, 1, v48
	v_lshrrev_b32_e32 v24, 1, v48
	v_and_b32_e32 v25, 3, v48
	v_and_or_b32 v22, v23, 8, v22
	v_and_or_b32 v23, v24, 4, v25
	v_and_b32_e32 v24, 0xfffff0, v16
	v_lshlrev_b32_e32 v25, 1, v16
	v_and_b32_e32 v17, 0x70, v80
	v_bfe_u32 v20, v20, 5, 2
	v_lshlrev_b32_e32 v26, 8, v48
	v_lshlrev_b32_e32 v16, 8, v16
	v_lshrrev_b32_e32 v22, 1, v22
	v_and_or_b32 v24, v25, 8, v24
	v_and_b32_e32 v27, 48, v21
	v_bitop3_b32 v25, v21, v26, v17 bitop3:0xde
	v_bitop3_b32 v16, v21, v16, v17 bitop3:0xde
	v_or_b32_e32 v17, v22, v20
	v_lshrrev_b32_e32 v21, 1, v24
	v_lshlrev_b32_e32 v23, 6, v23
	v_add_u32_e32 v205, 0, v16
	v_lshlrev_b32_e32 v16, 9, v17
	v_or_b32_e32 v17, v21, v20
	v_or3_b32 v16, v16, v23, v27
	v_lshlrev_b32_e32 v17, 9, v17
	v_lshlrev_b32_e32 v66, 4, v80
	v_or3_b32 v17, v17, v23, v27
	v_add_u32_e32 v206, 0, v16
	v_add_u32_e32 v204, 0, v25
	v_add_u32_e32 v207, 0, v17
	s_waitcnt vmcnt(0)
	s_mov_b64 s[2:3], 0x20000
	v_and_b32_e32 v81, 63, v80
	s_mov_b32 s12, s13
	s_mov_b32 s14, s13
	s_mov_b32 s15, s13
	s_mov_b32 s16, s13
	s_mov_b32 s17, s13
	s_mov_b32 s18, s13
	s_mov_b32 s19, s13
	s_mov_b32 s20, s13
	s_mov_b32 s21, s13
	s_mov_b32 s22, s13
	s_waitcnt vmcnt(11)
	s_waitcnt vmcnt(10)
	s_waitcnt vmcnt(9)
	s_waitcnt vmcnt(8)
	v_lshlrev_b32_e32 v12, 8, v155
	v_and_b32_e32 v13, 0x70, v66
	v_bitop3_b32 v0, v184, v12, v13 bitop3:0xde
	v_add_u32_e32 v183, 0, v0
	s_waitcnt lgkmcnt(0)
	s_barrier
; #define MFMA32(a, b, c) __builtin_amdgcn_mfma_f32_32x32x16_bf16((a), (b), (c), 0, 0, 0)
; DI float smA_max0(const f32x16& p0) {
;     float mx = p0[0];
; #pragma unroll
;     for (int r = 1; r < 16; ++r) mx = fmaxf(mx, p0[r]);
;     return mx;
; }
; DI float smA_max1(float mx, const f32x16& p1) {
; #pragma unroll
;     for (int r = 0; r < 16; ++r) mx = fmaxf(mx, p1[r]);
;     auto rr = __builtin_amdgcn_permlane32_swap(__float_as_uint(mx), __float_as_uint(mx), false, false);
;     return fmaxf(__uint_as_float(rr[0]), __uint_as_float(rr[1]));
; }
; template <int LO> DI void smA_exp(f32x16& p0) {
; #pragma unroll
;     for (int r = LO; r < LO + 8; ++r) p0[r] = __builtin_amdgcn_exp2f(p0[r]);
; }
; template <bool FIRST> DI void smB(f32x16& p0, f32x16& p1, float pmax, float& m_reg, float& alpha) {
;     if (!FIRST && __builtin_expect(__all(pmax <= ATHR2), 1)) { alpha = 1.f; }
;     else {
;         const float delta = FIRST ? pmax : fmaxf(pmax, 0.f);
;         alpha = __builtin_amdgcn_exp2f(-delta); m_reg += delta;
; #pragma unroll
;         for (int r = 0; r < 16; ++r) { p0[r] *= alpha; p1[r] -= delta; }
;     }
; }
; template <bool FIRST> DI void partialSM(f32x16& p0, f32x16& p1, float& m_reg, float& alpha) {
;     const float pmax = smA_max1(smA_max0(p0), p1);
;     smA_exp<0>(p0); smA_exp<8>(p0);
;     smB<FIRST>(p0, p1, pmax, m_reg, alpha);
; }
; DI void qkt(f32x16& p0, f32x16& p1, const char* Ks, const bf16x8* qr, float negm, int r32, int hi) {
; #pragma unroll
;     for (int i = 0; i < 16; ++i) { p0[i] = negm; p1[i] = negm; }
; #pragma unroll
;     for (int d0 = 0; d0 < 8; ++d0) { const int cb = (d0 * 16 + hi * 8) * 2;
;         bf16x8 b0 = *(const bf16x8*)(Ks + KSWZ(r32, cb));
;         bf16x8 b1 = *(const bf16x8*)(Ks + KSWZ(32 + r32, cb));
;         p0 = MFMA32(b0, qr[d0], p0);
;         p1 = MFMA32(b1, qr[d0], p1); }
; }
	ds_read_b128 v[0:3], v183 offset:32768
	ds_read_b128 v[4:7], v183 offset:40960
	s_waitcnt vmcnt(7) lgkmcnt(1)
	v_mfma_f32_32x32x16_bf16 v[32:47], v[0:3], v[140:143], 0
	v_or_b32_e32 v0, 32, v184
	v_bitop3_b32 v0, v0, v12, v13 bitop3:0xde
	v_add_u32_e32 v208, 0, v0
	v_lshl_add_u64 v[8:9], v[50:51], 0, s[2:3]
	v_lshl_add_u64 v[10:11], v[50:51], 0, s[56:57]
	s_add_i32 s2, 0, 0x10000
	s_cmp_lg_u32 0, -1
	s_waitcnt lgkmcnt(0)
	v_mfma_f32_32x32x16_bf16 v[16:31], v[4:7], v[140:143], 0
	ds_read_b128 v[0:3], v208 offset:32768
	ds_read_b128 v[4:7], v208 offset:40960
	s_mov_b32 s23, s13
	s_mov_b32 s24, s13
	s_mov_b32 s25, s13
	s_mov_b32 s26, s13
	s_mov_b32 s27, s13
	s_cselect_b32 s43, 0, 0
	s_waitcnt vmcnt(6) lgkmcnt(1)
	v_mfma_f32_32x32x16_bf16 v[32:47], v[0:3], v[136:139], v[32:47]
	v_or_b32_e32 v0, 64, v184
	v_bitop3_b32 v0, v0, v12, v13 bitop3:0xde
	v_add_u32_e32 v209, 0, v0
	s_mov_b32 s42, 2
	v_mov_b32_e32 v173, 0
	s_waitcnt lgkmcnt(0)
	v_mfma_f32_32x32x16_bf16 v[16:31], v[4:7], v[136:139], v[16:31]
	ds_read_b128 v[0:3], v209 offset:32768
	ds_read_b128 v[4:7], v209 offset:40960
	s_waitcnt vmcnt(5) lgkmcnt(1)
	v_mfma_f32_32x32x16_bf16 v[32:47], v[0:3], v[132:135], v[32:47]
	v_or_b32_e32 v0, 0x60, v184
	v_bitop3_b32 v0, v0, v12, v13 bitop3:0xde
	v_add_u32_e32 v210, 0, v0
	s_waitcnt lgkmcnt(0)
	v_mfma_f32_32x32x16_bf16 v[16:31], v[4:7], v[132:135], v[16:31]
	ds_read_b128 v[0:3], v210 offset:32768
	ds_read_b128 v[4:7], v210 offset:40960
	s_waitcnt vmcnt(4) lgkmcnt(1)
	v_mfma_f32_32x32x16_bf16 v[32:47], v[0:3], v[128:131], v[32:47]
	v_or_b32_e32 v0, 0x80, v184
	v_bitop3_b32 v0, v0, v12, v13 bitop3:0xde
	v_add_u32_e32 v211, 0, v0
	ds_read_b128 v[0:3], v211 offset:32768
	s_waitcnt lgkmcnt(1)
	v_mfma_f32_32x32x16_bf16 v[16:31], v[4:7], v[128:131], v[16:31]
	ds_read_b128 v[4:7], v211 offset:40960
	v_lshlrev_b32_e32 v8, 3, v81
	v_lshlrev_b32_e32 v10, 1, v80
	s_waitcnt vmcnt(7) lgkmcnt(1)
	v_mfma_f32_32x32x16_bf16 v[32:47], v[0:3], v[124:127], v[32:47]
	v_or_b32_e32 v0, 0xa0, v184
	v_bitop3_b32 v0, v0, v12, v13 bitop3:0xde
	v_add_u32_e32 v212, 0, v0
	ds_read_b128 v[0:3], v212 offset:32768
	s_waitcnt lgkmcnt(1)
	v_mfma_f32_32x32x16_bf16 v[16:31], v[4:7], v[124:127], v[16:31]
	v_and_b32_e32 v4, 0x3fffffc0, v80
	v_lshl_add_u32 v171, v4, 2, s2
	ds_read_b128 v[4:7], v212 offset:40960
	v_cmp_gt_u32_e64 s[2:3], 32, v81
	v_lshl_add_u32 v172, v155, 2, v171
	s_waitcnt vmcnt(6) lgkmcnt(1)
	v_mfma_f32_32x32x16_bf16 v[32:47], v[0:3], v[120:123], v[32:47]
	v_and_b32_e32 v0, 0xc0, v66
	v_and_or_b32 v9, v8, 24, v0
	v_or_b32_e32 v0, 0xc0, v184
	v_bitop3_b32 v0, v0, v12, v13 bitop3:0xde
	v_add_u32_e32 v213, 0, v0
	ds_read_b128 v[0:3], v213 offset:32768
	s_waitcnt lgkmcnt(1)
	v_mfma_f32_32x32x16_bf16 v[16:31], v[4:7], v[120:123], v[16:31]
	v_and_b32_e32 v4, 32, v10
	v_and_b32_e32 v5, 0x100, v8
	v_or3_b32 v82, v9, v4, v5
	ds_read_b128 v[4:7], v213 offset:40960
	v_add_u32_e32 v175, s43, v82
	s_addk_i32 s43, 0x4000
	v_add_u32_e32 v174, s43, v82
	s_waitcnt vmcnt(5) lgkmcnt(1)
	v_mfma_f32_32x32x16_bf16 v[32:47], v[0:3], v[116:119], v[32:47]
	v_or_b32_e32 v0, 0xe0, v184
	v_bitop3_b32 v0, v0, v12, v13 bitop3:0xde
	v_add_u32_e32 v214, 0, v0
	ds_read_b128 v[0:3], v214 offset:32768
	ds_read_b128 v[66:69], v214 offset:40960
	s_waitcnt vmcnt(0)
	s_waitcnt vmcnt(3)
	s_waitcnt vmcnt(2)
	s_waitcnt vmcnt(1)
	s_waitcnt vmcnt(0)
	s_waitcnt lgkmcnt(6)
	v_mfma_f32_32x32x16_bf16 v[16:31], v[4:7], v[116:119], v[16:31]
	s_waitcnt lgkmcnt(0)
	s_barrier
	v_mfma_f32_32x32x16_bf16 v[32:47], v[0:3], v[112:115], v[32:47]
	v_mov_b64_e32 v[0:1], s[12:13]
	v_mov_b64_e32 v[14:15], s[26:27]
	v_mov_b64_e32 v[2:3], s[14:15]
	v_mov_b64_e32 v[4:5], s[16:17]
	v_mov_b64_e32 v[6:7], s[18:19]
	v_mov_b64_e32 v[8:9], s[20:21]
	v_mov_b64_e32 v[10:11], s[22:23]
	v_mfma_f32_32x32x16_bf16 v[16:31], v[66:69], v[112:115], v[16:31]
	s_nop 3
	v_max_f32_e32 v66, v33, v33
	v_max_f32_e32 v67, v32, v32
	v_max_f32_e32 v66, v67, v66
	v_max3_f32 v66, v66, v34, v35
	v_max3_f32 v66, v66, v36, v37
	v_max3_f32 v66, v66, v38, v39
	v_max3_f32 v66, v66, v40, v41
	v_max3_f32 v66, v66, v42, v43
	v_max3_f32 v66, v66, v44, v45
	v_max3_f32 v66, v66, v46, v47
	v_max3_f32 v66, v66, v16, v17
	v_max3_f32 v66, v66, v18, v19
	v_max3_f32 v66, v66, v20, v21
	v_max3_f32 v66, v66, v22, v23
	v_max3_f32 v66, v66, v24, v25
	v_max3_f32 v66, v66, v26, v27
	v_max3_f32 v66, v66, v28, v29
	v_max3_f32 v66, v66, v30, v31
	v_mov_b32_e32 v67, v66
	s_nop 1
	v_permlane32_swap_b32_e32 v66, v67
	v_max_f32_e32 v50, v67, v67
	v_max_f32_e32 v51, v66, v66
	v_max_f32_e32 v50, v51, v50
	v_exp_f32_e32 v32, v32
	v_exp_f32_e64 v150, -v50
	v_exp_f32_e32 v33, v33
	v_exp_f32_e32 v34, v34
	v_exp_f32_e32 v35, v35
	v_exp_f32_e32 v36, v36
	v_exp_f32_e32 v37, v37
	v_exp_f32_e32 v38, v38
	v_exp_f32_e32 v39, v39
	v_exp_f32_e32 v40, v40
	v_exp_f32_e32 v42, v42
	v_exp_f32_e32 v44, v44
	v_exp_f32_e32 v46, v46
	v_exp_f32_e32 v47, v47
	v_exp_f32_e32 v45, v45
	v_exp_f32_e32 v43, v43
	v_exp_f32_e32 v41, v41
	v_sub_f32_e32 v66, v18, v50
	v_sub_f32_e32 v65, v17, v50
	v_sub_f32_e32 v64, v16, v50
	v_lshl_add_u64 v[16:17], s[68:69], 0, v[48:49]
	v_and_b32_e32 v18, 15, v80
	v_lshlrev_b64 v[16:17], 11, v[16:17]
	v_lshlrev_b32_e32 v18, 4, v18
	v_or3_b32 v16, v16, s72, v18
	v_mov_b64_e32 v[12:13], s[24:25]
	v_pk_mul_f32 v[146:147], v[46:47], v[150:151] op_sel_hi:[1,0]
	v_pk_mul_f32 v[160:161], v[44:45], v[150:151] op_sel_hi:[1,0]
	v_pk_mul_f32 v[164:165], v[42:43], v[150:151] op_sel_hi:[1,0]
	v_pk_mul_f32 v[168:169], v[40:41], v[150:151] op_sel_hi:[1,0]
	v_pk_mul_f32 v[156:157], v[38:39], v[150:151] op_sel_hi:[1,0]
	v_pk_mul_f32 v[158:159], v[36:37], v[150:151] op_sel_hi:[1,0]
	v_pk_mul_f32 v[162:163], v[34:35], v[150:151] op_sel_hi:[1,0]
	v_pk_mul_f32 v[166:167], v[32:33], v[150:151] op_sel_hi:[1,0]
	v_sub_f32_e32 v79, v31, v50
	v_sub_f32_e32 v78, v30, v50
	v_sub_f32_e32 v77, v29, v50
	v_sub_f32_e32 v76, v28, v50
	v_sub_f32_e32 v75, v27, v50
	v_sub_f32_e32 v74, v26, v50
	v_sub_f32_e32 v73, v25, v50
	v_sub_f32_e32 v72, v24, v50
	v_sub_f32_e32 v71, v23, v50
	v_sub_f32_e32 v70, v22, v50
	v_sub_f32_e32 v69, v21, v50
	v_sub_f32_e32 v68, v20, v50
	v_sub_f32_e32 v67, v19, v50
	v_add_f32_e32 v215, 0, v50
	v_lshl_add_u64 v[152:153], s[40:41], 0, v[16:17]
	v_mov_b64_e32 v[62:63], v[14:15]
	v_mov_b64_e32 v[30:31], v[14:15]
	v_mov_b64_e32 v[46:47], v[14:15]
	v_mov_b64_e32 v[60:61], v[12:13]
	v_mov_b64_e32 v[58:59], v[10:11]
	v_mov_b64_e32 v[56:57], v[8:9]
	v_mov_b64_e32 v[54:55], v[6:7]
	v_mov_b64_e32 v[52:53], v[4:5]
	v_mov_b64_e32 v[50:51], v[2:3]
	v_mov_b64_e32 v[48:49], v[0:1]
	v_mov_b64_e32 v[28:29], v[12:13]
	v_mov_b64_e32 v[26:27], v[10:11]
	v_mov_b64_e32 v[24:25], v[8:9]
	v_mov_b64_e32 v[22:23], v[6:7]
	v_mov_b64_e32 v[20:21], v[4:5]
	v_mov_b64_e32 v[18:19], v[2:3]
	v_mov_b64_e32 v[16:17], v[0:1]
	v_mov_b64_e32 v[44:45], v[12:13]
	v_mov_b64_e32 v[42:43], v[10:11]
	v_mov_b64_e32 v[40:41], v[8:9]
	v_mov_b64_e32 v[38:39], v[6:7]
	v_mov_b64_e32 v[36:37], v[4:5]
	v_mov_b64_e32 v[34:35], v[2:3]
	v_mov_b64_e32 v[32:33], v[0:1]
